# static s_setprio 1 for waves 0..3 in GEMM phases only (token mixers at priority 0)
# baseline (speedup 1.0000x reference)
; __global__ void __launch_bounds__(NTHREADS, 2) mk_fwd(Args args) {
;     ...
;         if (KON(2) && IN(pb + 1)) {
;             for (int it = blk; it < 256; it += G) p2_block(lds, PROJ, ATT, SGU, args.in[3] + l * 64, args.in[4] + l * 64, args.in[5] + l * 16, COS, SIN, args.in[6] + l * 1024, args.in[7] + l * 1024,
;                                                            args.in[8] + (size_t)l * 8 * 16384, args.in[9] + l * 1024, it, tid);
.LBB0_326:
	s_andn2_b64 vcc, exec, s[0:1]
	v_readlane_b32 s0, v248, 2
	v_readlane_b32 s1, v248, 3
	s_nop 1
	v_cndmask_b32_e64 v0, 0, 1, s[0:1]
	v_cmp_ne_u32_e64 s[70:71], 1, v0
	s_cbranch_vccnz .LBB0_413
	s_and_b64 vcc, exec, s[70:71]
	s_cbranch_vccnz .LBB0_346
	s_lshl_b32 s4, s64, 6
	v_readlane_b32 s36, v250, 2
	s_lshl_b64 s[0:1], s[4:5], 2
	v_readlane_b32 s38, v250, 4
	v_readlane_b32 s42, v250, 8
	v_readlane_b32 s39, v250, 5
	v_readlane_b32 s43, v250, 9
	s_add_u32 s38, s42, s0
	v_readlane_b32 s44, v250, 10
	s_addc_u32 s39, s43, s1
	v_readlane_b32 s45, v250, 11
	s_add_u32 s0, s44, s0
	s_addc_u32 s1, s45, s1
	s_lshl_b32 s4, s64, 4
	v_readlane_b32 s46, v250, 12
	s_lshl_b64 s[6:7], s[4:5], 2
	v_readlane_b32 s47, v250, 13
	s_add_u32 s63, s46, s6
	s_addc_u32 s78, s47, s7
	s_lshl_b32 s4, s64, 10
	v_readlane_b32 s48, v250, 14
	s_lshl_b64 s[6:7], s[4:5], 2
	v_readlane_b32 s37, v250, 3
	v_readlane_b32 s49, v250, 15
	s_add_u32 s36, s48, s6
	v_readlane_b32 s50, v250, 16
	s_addc_u32 s37, s49, s7
	v_readlane_b32 s40, v250, 6
	v_readlane_b32 s41, v250, 7
	v_readlane_b32 s51, v250, 17
	s_add_u32 s18, s50, s6
	s_addc_u32 s19, s51, s7
	s_lshl_b64 s[16:17], s[64:65], 19
	v_readlane_b32 s40, v250, 18
	v_readlane_b32 s41, v250, 19
	s_add_u32 s20, s40, s16
	v_readlane_b32 s42, v250, 20
	s_addc_u32 s21, s41, s17
	v_readlane_b32 s43, v250, 21
	s_add_u32 s22, s42, s6
	s_addc_u32 s23, s43, s7
	s_mov_b32 s2, s85
	s_setprio 0
	v_readlane_b32 s44, v250, 22
	v_readlane_b32 s45, v250, 23
	v_readlane_b32 s46, v250, 24
	v_readlane_b32 s47, v250, 25
	v_readlane_b32 s48, v250, 26
	v_readlane_b32 s49, v250, 27
	v_readlane_b32 s50, v250, 28
	v_readlane_b32 s51, v250, 29
	v_readlane_b32 s52, v250, 30
	v_readlane_b32 s53, v250, 31
	v_readlane_b32 s54, v250, 32
	v_readlane_b32 s55, v250, 33
	s_branch .LBB0_330

; __device__ __forceinline__ unsigned cvt_pk_bf16(float lo, float hi) { unsigned r; asm volatile("v_cvt_pk_bf16_f32 %0, %1, %2" : "=v"(r) : "v"(lo), "v"(hi)); return r; }
; __device__ __forceinline__ float bf_lo(unsigned w) { return __uint_as_float(w << 16); }
; __device__ __forceinline__ float bf_hi(unsigned w) { return __uint_as_float(w & 0xffff0000u); }
; __device__ __forceinline__ float gelu_f(float x) { const float y2 = 1.5957691216057308f * x * (1.0f + 0.044715f * x * x); return x * sigmoid_f(y2); }
; __device__ __forceinline__ void p2_block(LAS unsigned char* lds, const bf16_t* __restrict__ PROJ, bf16_t* __restrict__ ATT, bf16_t* __restrict__ SGU, const float* __restrict__ qn, const float* __restrict__ kn, ...
;     ...
;         const float bias = bsp[gg * 128 + irow];
;         const size_t grow = (size_t)b * pg8::SEQ + n * 128 + irow;
;         const bf16_t* up = PROJ + grow * pg8::IN_W + pg8::C_U + gg * 128 + 4 * fq; bf16_t* op = SGU + grow * 1024 + gg * 128 + 4 * fq;
; #pragma unroll
;         for (int dt = 0; dt < 8; ++dt) { const u32x2 uw = *(const u32x2*)(up + 16 * dt);
;             const float u0 = gelu_f(bf_lo(uw.x)), u1 = gelu_f(bf_hi(uw.x)), u2 = gelu_f(bf_lo(uw.y)), u3 = gelu_f(bf_hi(uw.y));
;             u32x2 ow; ow.x = cvt_pk_bf16(u0 * (acc[dt][0] + bias), u1 * (acc[dt][1] + bias)); ow.y = cvt_pk_bf16(u2 * (acc[dt][2] + bias), u3 * (acc[dt][3] + bias)); *(u32x2*)(op + 16 * dt) = ow; }
.Lsgu_epi:
	v_mov_b32_e32 v197, 0xbdd2d3e7
	s_waitcnt vmcnt(0)
	v_lshlrev_b32_e32 v34, 16, v218
	v_and_b32_e32 v35, 0xffff0000, v218
	v_lshlrev_b32_e32 v36, 16, v219
	v_and_b32_e32 v37, 0xffff0000, v219
	v_mul_f32_e32 v38, v34, v34
	v_mul_f32_e32 v39, v35, v35
	v_mul_f32_e32 v40, v36, v36
	v_mul_f32_e32 v41, v37, v37
	v_fmaak_f32 v38, v38, v197, 0xc0135761
	v_fmaak_f32 v39, v39, v197, 0xc0135761
	v_fmaak_f32 v40, v40, v197, 0xc0135761
	v_fmaak_f32 v41, v41, v197, 0xc0135761
	v_mul_f32_e32 v38, v38, v34
	v_mul_f32_e32 v39, v39, v35
	v_mul_f32_e32 v40, v40, v36
	v_mul_f32_e32 v41, v41, v37
	v_exp_f32_e32 v38, v38
	v_exp_f32_e32 v39, v39
	v_exp_f32_e32 v40, v40
	v_exp_f32_e32 v41, v41
	v_add_f32_e32 v38, 1.0, v38
	v_add_f32_e32 v39, 1.0, v39
	v_add_f32_e32 v40, 1.0, v40
	v_add_f32_e32 v41, 1.0, v41
	v_rcp_f32_e32 v38, v38
	v_rcp_f32_e32 v39, v39
	v_rcp_f32_e32 v40, v40
	v_rcp_f32_e32 v41, v41
	v_mul_f32_e32 v34, v38, v34
	v_mul_f32_e32 v35, v39, v35
	v_mul_f32_e32 v36, v40, v36
	v_mul_f32_e32 v37, v41, v37
	v_mul_f32_e32 v46, v2, v34
	v_mul_f32_e32 v47, v3, v35
	v_mul_f32_e32 v48, v4, v36
	v_mul_f32_e32 v49, v5, v37
	v_cvt_pk_bf16_f32 v50, v46, v47
	v_cvt_pk_bf16_f32 v51, v48, v49
	global_store_dwordx2 v182, v[50:51], s[12:13] offset:0
	v_lshlrev_b32_e32 v34, 16, v220
	v_and_b32_e32 v35, 0xffff0000, v220
	v_lshlrev_b32_e32 v36, 16, v221
	v_and_b32_e32 v37, 0xffff0000, v221
	v_mul_f32_e32 v38, v34, v34
	v_mul_f32_e32 v39, v35, v35
	v_mul_f32_e32 v40, v36, v36
	v_mul_f32_e32 v41, v37, v37
	v_fmaak_f32 v38, v38, v197, 0xc0135761
	v_fmaak_f32 v39, v39, v197, 0xc0135761
	v_fmaak_f32 v40, v40, v197, 0xc0135761
	v_fmaak_f32 v41, v41, v197, 0xc0135761
	v_mul_f32_e32 v38, v38, v34
	v_mul_f32_e32 v39, v39, v35
	v_mul_f32_e32 v40, v40, v36
	v_mul_f32_e32 v41, v41, v37
	v_exp_f32_e32 v38, v38
	v_exp_f32_e32 v39, v39
	v_exp_f32_e32 v40, v40
	v_exp_f32_e32 v41, v41
	v_add_f32_e32 v38, 1.0, v38
	v_add_f32_e32 v39, 1.0, v39
	v_add_f32_e32 v40, 1.0, v40
	v_add_f32_e32 v41, 1.0, v41
	v_rcp_f32_e32 v38, v38
	v_rcp_f32_e32 v39, v39
	v_rcp_f32_e32 v40, v40
	v_rcp_f32_e32 v41, v41
	v_mul_f32_e32 v34, v38, v34
	v_mul_f32_e32 v35, v39, v35
	v_mul_f32_e32 v36, v40, v36
	v_mul_f32_e32 v37, v41, v37
	v_mul_f32_e32 v46, v6, v34
	v_mul_f32_e32 v47, v7, v35
	v_mul_f32_e32 v48, v8, v36
	v_mul_f32_e32 v49, v9, v37
	v_cvt_pk_bf16_f32 v50, v46, v47
	v_cvt_pk_bf16_f32 v51, v48, v49
	global_store_dwordx2 v182, v[50:51], s[12:13] offset:32
	v_lshlrev_b32_e32 v34, 16, v222
	v_and_b32_e32 v35, 0xffff0000, v222
	v_lshlrev_b32_e32 v36, 16, v223
	v_and_b32_e32 v37, 0xffff0000, v223
	v_mul_f32_e32 v38, v34, v34
	v_mul_f32_e32 v39, v35, v35
	v_mul_f32_e32 v40, v36, v36
	v_mul_f32_e32 v41, v37, v37
	v_fmaak_f32 v38, v38, v197, 0xc0135761
	v_fmaak_f32 v39, v39, v197, 0xc0135761
	v_fmaak_f32 v40, v40, v197, 0xc0135761
	v_fmaak_f32 v41, v41, v197, 0xc0135761
	v_mul_f32_e32 v38, v38, v34
	v_mul_f32_e32 v39, v39, v35
	v_mul_f32_e32 v40, v40, v36
	v_mul_f32_e32 v41, v41, v37
	v_exp_f32_e32 v38, v38
	v_exp_f32_e32 v39, v39
	v_exp_f32_e32 v40, v40
	v_exp_f32_e32 v41, v41
	v_add_f32_e32 v38, 1.0, v38
	v_add_f32_e32 v39, 1.0, v39
	v_add_f32_e32 v40, 1.0, v40
	v_add_f32_e32 v41, 1.0, v41
	v_rcp_f32_e32 v38, v38
	v_rcp_f32_e32 v39, v39
	v_rcp_f32_e32 v40, v40
	v_rcp_f32_e32 v41, v41
	v_mul_f32_e32 v34, v38, v34
	v_mul_f32_e32 v35, v39, v35
	v_mul_f32_e32 v36, v40, v36
	v_mul_f32_e32 v37, v41, v37
	v_mul_f32_e32 v46, v10, v34
	v_mul_f32_e32 v47, v11, v35
	v_mul_f32_e32 v48, v12, v36
	v_mul_f32_e32 v49, v13, v37
	v_cvt_pk_bf16_f32 v50, v46, v47
	v_cvt_pk_bf16_f32 v51, v48, v49
	global_store_dwordx2 v182, v[50:51], s[12:13] offset:64
	v_lshlrev_b32_e32 v34, 16, v224
	v_and_b32_e32 v35, 0xffff0000, v224
	v_lshlrev_b32_e32 v36, 16, v225
	v_and_b32_e32 v37, 0xffff0000, v225
	v_mul_f32_e32 v38, v34, v34
	v_mul_f32_e32 v39, v35, v35
	v_mul_f32_e32 v40, v36, v36
	v_mul_f32_e32 v41, v37, v37
	v_fmaak_f32 v38, v38, v197, 0xc0135761
	v_fmaak_f32 v39, v39, v197, 0xc0135761
	v_fmaak_f32 v40, v40, v197, 0xc0135761
	v_fmaak_f32 v41, v41, v197, 0xc0135761
	v_mul_f32_e32 v38, v38, v34
	v_mul_f32_e32 v39, v39, v35
	v_mul_f32_e32 v40, v40, v36
	v_mul_f32_e32 v41, v41, v37
	v_exp_f32_e32 v38, v38
	v_exp_f32_e32 v39, v39
	v_exp_f32_e32 v40, v40
	v_exp_f32_e32 v41, v41
	v_add_f32_e32 v38, 1.0, v38
	v_add_f32_e32 v39, 1.0, v39
	v_add_f32_e32 v40, 1.0, v40
	v_add_f32_e32 v41, 1.0, v41
	v_rcp_f32_e32 v38, v38
	v_rcp_f32_e32 v39, v39
	v_rcp_f32_e32 v40, v40
	v_rcp_f32_e32 v41, v41
	v_mul_f32_e32 v34, v38, v34
	v_mul_f32_e32 v35, v39, v35
	v_mul_f32_e32 v36, v40, v36
	v_mul_f32_e32 v37, v41, v37
	v_mul_f32_e32 v46, v14, v34
	v_mul_f32_e32 v47, v15, v35
	v_mul_f32_e32 v48, v16, v36
	v_mul_f32_e32 v49, v17, v37
	v_cvt_pk_bf16_f32 v50, v46, v47
	v_cvt_pk_bf16_f32 v51, v48, v49
	global_store_dwordx2 v182, v[50:51], s[12:13] offset:96
	v_lshlrev_b32_e32 v34, 16, v226
	v_and_b32_e32 v35, 0xffff0000, v226
	v_lshlrev_b32_e32 v36, 16, v227
	v_and_b32_e32 v37, 0xffff0000, v227
	v_mul_f32_e32 v38, v34, v34
	v_mul_f32_e32 v39, v35, v35
	v_mul_f32_e32 v40, v36, v36
	v_mul_f32_e32 v41, v37, v37
	v_fmaak_f32 v38, v38, v197, 0xc0135761
	v_fmaak_f32 v39, v39, v197, 0xc0135761
	v_fmaak_f32 v40, v40, v197, 0xc0135761
	v_fmaak_f32 v41, v41, v197, 0xc0135761
	v_mul_f32_e32 v38, v38, v34
	v_mul_f32_e32 v39, v39, v35
	v_mul_f32_e32 v40, v40, v36
	v_mul_f32_e32 v41, v41, v37
	v_exp_f32_e32 v38, v38
	v_exp_f32_e32 v39, v39
	v_exp_f32_e32 v40, v40
	v_exp_f32_e32 v41, v41
	v_add_f32_e32 v38, 1.0, v38
	v_add_f32_e32 v39, 1.0, v39
	v_add_f32_e32 v40, 1.0, v40
	v_add_f32_e32 v41, 1.0, v41
	v_rcp_f32_e32 v38, v38
	v_rcp_f32_e32 v39, v39
	v_rcp_f32_e32 v40, v40
; __device__ __forceinline__ unsigned cvt_pk_bf16(float lo, float hi) { unsigned r; asm volatile("v_cvt_pk_bf16_f32 %0, %1, %2" : "=v"(r) : "v"(lo), "v"(hi)); return r; }
; __device__ __forceinline__ float bf_lo(unsigned w) { return __uint_as_float(w << 16); }
; __device__ __forceinline__ float bf_hi(unsigned w) { return __uint_as_float(w & 0xffff0000u); }
; __device__ __forceinline__ float gelu_f(float x) { const float y2 = 1.5957691216057308f * x * (1.0f + 0.044715f * x * x); return x * sigmoid_f(y2); }
; __device__ __forceinline__ void p2_block(LAS unsigned char* lds, const bf16_t* __restrict__ PROJ, bf16_t* __restrict__ ATT, bf16_t* __restrict__ SGU, const float* __restrict__ qn, const float* __restrict__ kn, ...
;     ...
;         const float bias = bsp[gg * 128 + irow];
;         const size_t grow = (size_t)b * pg8::SEQ + n * 128 + irow;
;         const bf16_t* up = PROJ + grow * pg8::IN_W + pg8::C_U + gg * 128 + 4 * fq; bf16_t* op = SGU + grow * 1024 + gg * 128 + 4 * fq;
; #pragma unroll
;         for (int dt = 0; dt < 8; ++dt) { const u32x2 uw = *(const u32x2*)(up + 16 * dt);
;             const float u0 = gelu_f(bf_lo(uw.x)), u1 = gelu_f(bf_hi(uw.x)), u2 = gelu_f(bf_lo(uw.y)), u3 = gelu_f(bf_hi(uw.y));
;             u32x2 ow; ow.x = cvt_pk_bf16(u0 * (acc[dt][0] + bias), u1 * (acc[dt][1] + bias)); ow.y = cvt_pk_bf16(u2 * (acc[dt][2] + bias), u3 * (acc[dt][3] + bias)); *(u32x2*)(op + 16 * dt) = ow; }
	v_rcp_f32_e32 v41, v41
	v_mul_f32_e32 v34, v38, v34
	v_mul_f32_e32 v35, v39, v35
	v_mul_f32_e32 v36, v40, v36
	v_mul_f32_e32 v37, v41, v37
	v_mul_f32_e32 v46, v18, v34
	v_mul_f32_e32 v47, v19, v35
	v_mul_f32_e32 v48, v20, v36
	v_mul_f32_e32 v49, v21, v37
	v_cvt_pk_bf16_f32 v50, v46, v47
	v_cvt_pk_bf16_f32 v51, v48, v49
	global_store_dwordx2 v182, v[50:51], s[12:13] offset:128
	v_lshlrev_b32_e32 v34, 16, v228
	v_and_b32_e32 v35, 0xffff0000, v228
	v_lshlrev_b32_e32 v36, 16, v229
	v_and_b32_e32 v37, 0xffff0000, v229
	v_mul_f32_e32 v38, v34, v34
	v_mul_f32_e32 v39, v35, v35
	v_mul_f32_e32 v40, v36, v36
	v_mul_f32_e32 v41, v37, v37
	v_fmaak_f32 v38, v38, v197, 0xc0135761
	v_fmaak_f32 v39, v39, v197, 0xc0135761
	v_fmaak_f32 v40, v40, v197, 0xc0135761
	v_fmaak_f32 v41, v41, v197, 0xc0135761
	v_mul_f32_e32 v38, v38, v34
	v_mul_f32_e32 v39, v39, v35
	v_mul_f32_e32 v40, v40, v36
	v_mul_f32_e32 v41, v41, v37
	v_exp_f32_e32 v38, v38
	v_exp_f32_e32 v39, v39
	v_exp_f32_e32 v40, v40
	v_exp_f32_e32 v41, v41
	v_add_f32_e32 v38, 1.0, v38
	v_add_f32_e32 v39, 1.0, v39
	v_add_f32_e32 v40, 1.0, v40
	v_add_f32_e32 v41, 1.0, v41
	v_rcp_f32_e32 v38, v38
	v_rcp_f32_e32 v39, v39
	v_rcp_f32_e32 v40, v40
	v_rcp_f32_e32 v41, v41
	v_mul_f32_e32 v34, v38, v34
	v_mul_f32_e32 v35, v39, v35
	v_mul_f32_e32 v36, v40, v36
	v_mul_f32_e32 v37, v41, v37
	v_mul_f32_e32 v46, v22, v34
	v_mul_f32_e32 v47, v23, v35
	v_mul_f32_e32 v48, v24, v36
	v_mul_f32_e32 v49, v25, v37
	v_cvt_pk_bf16_f32 v50, v46, v47
	v_cvt_pk_bf16_f32 v51, v48, v49
	global_store_dwordx2 v182, v[50:51], s[12:13] offset:160
	v_lshlrev_b32_e32 v34, 16, v230
	v_and_b32_e32 v35, 0xffff0000, v230
	v_lshlrev_b32_e32 v36, 16, v231
	v_and_b32_e32 v37, 0xffff0000, v231
	v_mul_f32_e32 v38, v34, v34
	v_mul_f32_e32 v39, v35, v35
	v_mul_f32_e32 v40, v36, v36
	v_mul_f32_e32 v41, v37, v37
	v_fmaak_f32 v38, v38, v197, 0xc0135761
	v_fmaak_f32 v39, v39, v197, 0xc0135761
	v_fmaak_f32 v40, v40, v197, 0xc0135761
	v_fmaak_f32 v41, v41, v197, 0xc0135761
	v_mul_f32_e32 v38, v38, v34
	v_mul_f32_e32 v39, v39, v35
	v_mul_f32_e32 v40, v40, v36
	v_mul_f32_e32 v41, v41, v37
	v_exp_f32_e32 v38, v38
	v_exp_f32_e32 v39, v39
	v_exp_f32_e32 v40, v40
	v_exp_f32_e32 v41, v41
	v_add_f32_e32 v38, 1.0, v38
	v_add_f32_e32 v39, 1.0, v39
	v_add_f32_e32 v40, 1.0, v40
	v_add_f32_e32 v41, 1.0, v41
	v_rcp_f32_e32 v38, v38
	v_rcp_f32_e32 v39, v39
	v_rcp_f32_e32 v40, v40
	v_rcp_f32_e32 v41, v41
	v_mul_f32_e32 v34, v38, v34
	v_mul_f32_e32 v35, v39, v35
	v_mul_f32_e32 v36, v40, v36
	v_mul_f32_e32 v37, v41, v37
	v_mul_f32_e32 v46, v26, v34
	v_mul_f32_e32 v47, v27, v35
	v_mul_f32_e32 v48, v28, v36
	v_mul_f32_e32 v49, v29, v37
	v_cvt_pk_bf16_f32 v50, v46, v47
	v_cvt_pk_bf16_f32 v51, v48, v49
	global_store_dwordx2 v182, v[50:51], s[12:13] offset:192
	v_lshlrev_b32_e32 v34, 16, v232
	v_and_b32_e32 v35, 0xffff0000, v232
	v_lshlrev_b32_e32 v36, 16, v233
	v_and_b32_e32 v37, 0xffff0000, v233
	v_mul_f32_e32 v38, v34, v34
	v_mul_f32_e32 v39, v35, v35
	v_mul_f32_e32 v40, v36, v36
	v_mul_f32_e32 v41, v37, v37
	v_fmaak_f32 v38, v38, v197, 0xc0135761
	v_fmaak_f32 v39, v39, v197, 0xc0135761
	v_fmaak_f32 v40, v40, v197, 0xc0135761
	v_fmaak_f32 v41, v41, v197, 0xc0135761
	v_mul_f32_e32 v38, v38, v34
	v_mul_f32_e32 v39, v39, v35
	v_mul_f32_e32 v40, v40, v36
	v_mul_f32_e32 v41, v41, v37
	v_exp_f32_e32 v38, v38
	v_exp_f32_e32 v39, v39
	v_exp_f32_e32 v40, v40
	v_exp_f32_e32 v41, v41
	v_add_f32_e32 v38, 1.0, v38
	v_add_f32_e32 v39, 1.0, v39
	v_add_f32_e32 v40, 1.0, v40
	v_add_f32_e32 v41, 1.0, v41
	v_rcp_f32_e32 v38, v38
	v_rcp_f32_e32 v39, v39
	v_rcp_f32_e32 v40, v40
	v_rcp_f32_e32 v41, v41
	v_mul_f32_e32 v34, v38, v34
	v_mul_f32_e32 v35, v39, v35
	v_mul_f32_e32 v36, v40, v36
	v_mul_f32_e32 v37, v41, v37
	v_mul_f32_e32 v46, v30, v34
	v_mul_f32_e32 v47, v31, v35
	v_mul_f32_e32 v48, v32, v36
	v_mul_f32_e32 v49, v33, v37
	v_cvt_pk_bf16_f32 v50, v46, v47
	v_cvt_pk_bf16_f32 v51, v48, v49
	global_store_dwordx2 v182, v[50:51], s[12:13] offset:224
	v_lshlrev_b32_e32 v34, 16, v234
	v_and_b32_e32 v35, 0xffff0000, v234
	v_lshlrev_b32_e32 v36, 16, v235
	v_and_b32_e32 v37, 0xffff0000, v235
	v_mul_f32_e32 v38, v34, v34
	v_mul_f32_e32 v39, v35, v35
	v_mul_f32_e32 v40, v36, v36
	v_mul_f32_e32 v41, v37, v37
	v_fmaak_f32 v38, v38, v197, 0xc0135761
	v_fmaak_f32 v39, v39, v197, 0xc0135761
	v_fmaak_f32 v40, v40, v197, 0xc0135761
	v_fmaak_f32 v41, v41, v197, 0xc0135761
	v_mul_f32_e32 v38, v38, v34
	v_mul_f32_e32 v39, v39, v35
	v_mul_f32_e32 v40, v40, v36
	v_mul_f32_e32 v41, v41, v37
	v_exp_f32_e32 v38, v38
	v_exp_f32_e32 v39, v39
	v_exp_f32_e32 v40, v40
	v_exp_f32_e32 v41, v41
	v_add_f32_e32 v38, 1.0, v38
	v_add_f32_e32 v39, 1.0, v39
	v_add_f32_e32 v40, 1.0, v40
	v_add_f32_e32 v41, 1.0, v41
	v_rcp_f32_e32 v38, v38
	v_rcp_f32_e32 v39, v39
	v_rcp_f32_e32 v40, v40
	v_rcp_f32_e32 v41, v41
	v_mul_f32_e32 v34, v38, v34
	v_mul_f32_e32 v35, v39, v35
	v_mul_f32_e32 v36, v40, v36
	v_mul_f32_e32 v37, v41, v37
	v_mul_f32_e32 v46, v114, v34
	v_mul_f32_e32 v47, v115, v35
	v_mul_f32_e32 v48, v116, v36
	v_mul_f32_e32 v49, v117, v37
	v_cvt_pk_bf16_f32 v50, v46, v47
	v_cvt_pk_bf16_f32 v51, v48, v49
	global_store_dwordx2 v182, v[50:51], s[12:13] offset:256
	v_lshlrev_b32_e32 v34, 16, v236
	v_and_b32_e32 v35, 0xffff0000, v236
	v_lshlrev_b32_e32 v36, 16, v237
	v_and_b32_e32 v37, 0xffff0000, v237
	v_mul_f32_e32 v38, v34, v34
	v_mul_f32_e32 v39, v35, v35
	v_mul_f32_e32 v40, v36, v36
	v_mul_f32_e32 v41, v37, v37
	v_fmaak_f32 v38, v38, v197, 0xc0135761
	v_fmaak_f32 v39, v39, v197, 0xc0135761
	v_fmaak_f32 v40, v40, v197, 0xc0135761
	v_fmaak_f32 v41, v41, v197, 0xc0135761
	v_mul_f32_e32 v38, v38, v34
	v_mul_f32_e32 v39, v39, v35
; __device__ __forceinline__ unsigned cvt_pk_bf16(float lo, float hi) { unsigned r; asm volatile("v_cvt_pk_bf16_f32 %0, %1, %2" : "=v"(r) : "v"(lo), "v"(hi)); return r; }
; __device__ __forceinline__ float bf_lo(unsigned w) { return __uint_as_float(w << 16); }
; __device__ __forceinline__ float bf_hi(unsigned w) { return __uint_as_float(w & 0xffff0000u); }
; __device__ __forceinline__ float gelu_f(float x) { const float y2 = 1.5957691216057308f * x * (1.0f + 0.044715f * x * x); return x * sigmoid_f(y2); }
; __device__ __forceinline__ void p2_block(LAS unsigned char* lds, const bf16_t* __restrict__ PROJ, bf16_t* __restrict__ ATT, bf16_t* __restrict__ SGU, const float* __restrict__ qn, const float* __restrict__ kn, ...
;     ...
;         for (int dt = 0; dt < 8; ++dt) { const u32x2 uw = *(const u32x2*)(up + 16 * dt);
;             const float u0 = gelu_f(bf_lo(uw.x)), u1 = gelu_f(bf_hi(uw.x)), u2 = gelu_f(bf_lo(uw.y)), u3 = gelu_f(bf_hi(uw.y));
;             u32x2 ow; ow.x = cvt_pk_bf16(u0 * (acc[dt][0] + bias), u1 * (acc[dt][1] + bias)); ow.y = cvt_pk_bf16(u2 * (acc[dt][2] + bias), u3 * (acc[dt][3] + bias)); *(u32x2*)(op + 16 * dt) = ow; }
	v_mul_f32_e32 v40, v40, v36
	v_mul_f32_e32 v41, v41, v37
	v_exp_f32_e32 v38, v38
	v_exp_f32_e32 v39, v39
	v_exp_f32_e32 v40, v40
	v_exp_f32_e32 v41, v41
	v_add_f32_e32 v38, 1.0, v38
	v_add_f32_e32 v39, 1.0, v39
	v_add_f32_e32 v40, 1.0, v40
	v_add_f32_e32 v41, 1.0, v41
	v_rcp_f32_e32 v38, v38
	v_rcp_f32_e32 v39, v39
	v_rcp_f32_e32 v40, v40
	v_rcp_f32_e32 v41, v41
	v_mul_f32_e32 v34, v38, v34
	v_mul_f32_e32 v35, v39, v35
	v_mul_f32_e32 v36, v40, v36
	v_mul_f32_e32 v37, v41, v37
	v_mul_f32_e32 v46, v118, v34
	v_mul_f32_e32 v47, v119, v35
	v_mul_f32_e32 v48, v120, v36
	v_mul_f32_e32 v49, v121, v37
	v_cvt_pk_bf16_f32 v50, v46, v47
	v_cvt_pk_bf16_f32 v51, v48, v49
	global_store_dwordx2 v182, v[50:51], s[12:13] offset:288
	v_lshlrev_b32_e32 v34, 16, v238
	v_and_b32_e32 v35, 0xffff0000, v238
	v_lshlrev_b32_e32 v36, 16, v239
	v_and_b32_e32 v37, 0xffff0000, v239
	v_mul_f32_e32 v38, v34, v34
	v_mul_f32_e32 v39, v35, v35
	v_mul_f32_e32 v40, v36, v36
	v_mul_f32_e32 v41, v37, v37
	v_fmaak_f32 v38, v38, v197, 0xc0135761
	v_fmaak_f32 v39, v39, v197, 0xc0135761
	v_fmaak_f32 v40, v40, v197, 0xc0135761
	v_fmaak_f32 v41, v41, v197, 0xc0135761
	v_mul_f32_e32 v38, v38, v34
	v_mul_f32_e32 v39, v39, v35
	v_mul_f32_e32 v40, v40, v36
	v_mul_f32_e32 v41, v41, v37
	v_exp_f32_e32 v38, v38
	v_exp_f32_e32 v39, v39
	v_exp_f32_e32 v40, v40
	v_exp_f32_e32 v41, v41
	v_add_f32_e32 v38, 1.0, v38
	v_add_f32_e32 v39, 1.0, v39
	v_add_f32_e32 v40, 1.0, v40
	v_add_f32_e32 v41, 1.0, v41
	v_rcp_f32_e32 v38, v38
	v_rcp_f32_e32 v39, v39
	v_rcp_f32_e32 v40, v40
	v_rcp_f32_e32 v41, v41
	v_mul_f32_e32 v34, v38, v34
	v_mul_f32_e32 v35, v39, v35
	v_mul_f32_e32 v36, v40, v36
	v_mul_f32_e32 v37, v41, v37
	v_mul_f32_e32 v46, v122, v34
	v_mul_f32_e32 v47, v123, v35
	v_mul_f32_e32 v48, v124, v36
	v_mul_f32_e32 v49, v125, v37
	v_cvt_pk_bf16_f32 v50, v46, v47
	v_cvt_pk_bf16_f32 v51, v48, v49
	global_store_dwordx2 v182, v[50:51], s[12:13] offset:320
	v_lshlrev_b32_e32 v34, 16, v240
	v_and_b32_e32 v35, 0xffff0000, v240
	v_lshlrev_b32_e32 v36, 16, v241
	v_and_b32_e32 v37, 0xffff0000, v241
	v_mul_f32_e32 v38, v34, v34
	v_mul_f32_e32 v39, v35, v35
	v_mul_f32_e32 v40, v36, v36
	v_mul_f32_e32 v41, v37, v37
	v_fmaak_f32 v38, v38, v197, 0xc0135761
	v_fmaak_f32 v39, v39, v197, 0xc0135761
	v_fmaak_f32 v40, v40, v197, 0xc0135761
	v_fmaak_f32 v41, v41, v197, 0xc0135761
	v_mul_f32_e32 v38, v38, v34
	v_mul_f32_e32 v39, v39, v35
	v_mul_f32_e32 v40, v40, v36
	v_mul_f32_e32 v41, v41, v37
	v_exp_f32_e32 v38, v38
	v_exp_f32_e32 v39, v39
	v_exp_f32_e32 v40, v40
	v_exp_f32_e32 v41, v41
	v_add_f32_e32 v38, 1.0, v38
	v_add_f32_e32 v39, 1.0, v39
	v_add_f32_e32 v40, 1.0, v40
	v_add_f32_e32 v41, 1.0, v41
	v_rcp_f32_e32 v38, v38
	v_rcp_f32_e32 v39, v39
	v_rcp_f32_e32 v40, v40
	v_rcp_f32_e32 v41, v41
	v_mul_f32_e32 v34, v38, v34
	v_mul_f32_e32 v35, v39, v35
	v_mul_f32_e32 v36, v40, v36
	v_mul_f32_e32 v37, v41, v37
	v_mul_f32_e32 v46, v126, v34
	v_mul_f32_e32 v47, v127, v35
	v_mul_f32_e32 v48, v128, v36
	v_mul_f32_e32 v49, v129, v37
	v_cvt_pk_bf16_f32 v50, v46, v47
	v_cvt_pk_bf16_f32 v51, v48, v49
	global_store_dwordx2 v182, v[50:51], s[12:13] offset:352
	v_lshlrev_b32_e32 v34, 16, v242
	v_and_b32_e32 v35, 0xffff0000, v242
	v_lshlrev_b32_e32 v36, 16, v243
	v_and_b32_e32 v37, 0xffff0000, v243
	v_mul_f32_e32 v38, v34, v34
	v_mul_f32_e32 v39, v35, v35
	v_mul_f32_e32 v40, v36, v36
	v_mul_f32_e32 v41, v37, v37
	v_fmaak_f32 v38, v38, v197, 0xc0135761
	v_fmaak_f32 v39, v39, v197, 0xc0135761
	v_fmaak_f32 v40, v40, v197, 0xc0135761
	v_fmaak_f32 v41, v41, v197, 0xc0135761
	v_mul_f32_e32 v38, v38, v34
	v_mul_f32_e32 v39, v39, v35
	v_mul_f32_e32 v40, v40, v36
	v_mul_f32_e32 v41, v41, v37
	v_exp_f32_e32 v38, v38
	v_exp_f32_e32 v39, v39
	v_exp_f32_e32 v40, v40
	v_exp_f32_e32 v41, v41
	v_add_f32_e32 v38, 1.0, v38
	v_add_f32_e32 v39, 1.0, v39
	v_add_f32_e32 v40, 1.0, v40
	v_add_f32_e32 v41, 1.0, v41
	v_rcp_f32_e32 v38, v38
	v_rcp_f32_e32 v39, v39
	v_rcp_f32_e32 v40, v40
	v_rcp_f32_e32 v41, v41
	v_mul_f32_e32 v34, v38, v34
	v_mul_f32_e32 v35, v39, v35
	v_mul_f32_e32 v36, v40, v36
	v_mul_f32_e32 v37, v41, v37
	v_mul_f32_e32 v46, v130, v34
	v_mul_f32_e32 v47, v131, v35
	v_mul_f32_e32 v48, v132, v36
	v_mul_f32_e32 v49, v133, v37
	v_cvt_pk_bf16_f32 v50, v46, v47
	v_cvt_pk_bf16_f32 v51, v48, v49
	global_store_dwordx2 v182, v[50:51], s[12:13] offset:384
	v_lshlrev_b32_e32 v34, 16, v244
	v_and_b32_e32 v35, 0xffff0000, v244
	v_lshlrev_b32_e32 v36, 16, v245
	v_and_b32_e32 v37, 0xffff0000, v245
	v_mul_f32_e32 v38, v34, v34
	v_mul_f32_e32 v39, v35, v35
	v_mul_f32_e32 v40, v36, v36
; __device__ __forceinline__ unsigned cvt_pk_bf16(float lo, float hi) { unsigned r; asm volatile("v_cvt_pk_bf16_f32 %0, %1, %2" : "=v"(r) : "v"(lo), "v"(hi)); return r; }
; __device__ __forceinline__ float bf_lo(unsigned w) { return __uint_as_float(w << 16); }
; __device__ __forceinline__ float bf_hi(unsigned w) { return __uint_as_float(w & 0xffff0000u); }
; __device__ __forceinline__ float gelu_f(float x) { const float y2 = 1.5957691216057308f * x * (1.0f + 0.044715f * x * x); return x * sigmoid_f(y2); }
; #define SEAM(k) do { if (IN(k) && IN((k) + 1)) { if (hi > 4096) cg::this_grid().sync(); else xcd_barrier(bar); } } while (0)
; __device__ __forceinline__ void p2_block(LAS unsigned char* lds, const bf16_t* __restrict__ PROJ, bf16_t* __restrict__ ATT, bf16_t* __restrict__ SGU, const float* __restrict__ qn, const float* __restrict__ kn, ...
;     ...
;         for (int dt = 0; dt < 8; ++dt) { const u32x2 uw = *(const u32x2*)(up + 16 * dt);
;             const float u0 = gelu_f(bf_lo(uw.x)), u1 = gelu_f(bf_hi(uw.x)), u2 = gelu_f(bf_lo(uw.y)), u3 = gelu_f(bf_hi(uw.y));
;             u32x2 ow; ow.x = cvt_pk_bf16(u0 * (acc[dt][0] + bias), u1 * (acc[dt][1] + bias)); ow.y = cvt_pk_bf16(u2 * (acc[dt][2] + bias), u3 * (acc[dt][3] + bias)); *(u32x2*)(op + 16 * dt) = ow; }
;     }
;     __syncthreads();
; __global__ void __launch_bounds__(NTHREADS, 2) mk_fwd(Args args) {
;     ...
;             for (int it = blk; it < 256; it += G) p2_block(lds, PROJ, ATT, SGU, args.in[3] + l * 64, args.in[4] + l * 64, args.in[5] + l * 16, COS, SIN, args.in[6] + l * 1024, args.in[7] + l * 1024,
;                                                            args.in[8] + (size_t)l * 8 * 16384, args.in[9] + l * 1024, it, tid);
;         }
;         SEAM(pb + 1);
	v_mul_f32_e32 v41, v37, v37
	v_fmaak_f32 v38, v38, v197, 0xc0135761
	v_fmaak_f32 v39, v39, v197, 0xc0135761
	v_fmaak_f32 v40, v40, v197, 0xc0135761
	v_fmaak_f32 v41, v41, v197, 0xc0135761
	v_mul_f32_e32 v38, v38, v34
	v_mul_f32_e32 v39, v39, v35
	v_mul_f32_e32 v40, v40, v36
	v_mul_f32_e32 v41, v41, v37
	v_exp_f32_e32 v38, v38
	v_exp_f32_e32 v39, v39
	v_exp_f32_e32 v40, v40
	v_exp_f32_e32 v41, v41
	v_add_f32_e32 v38, 1.0, v38
	v_add_f32_e32 v39, 1.0, v39
	v_add_f32_e32 v40, 1.0, v40
	v_add_f32_e32 v41, 1.0, v41
	v_rcp_f32_e32 v38, v38
	v_rcp_f32_e32 v39, v39
	v_rcp_f32_e32 v40, v40
	v_rcp_f32_e32 v41, v41
	v_mul_f32_e32 v34, v38, v34
	v_mul_f32_e32 v35, v39, v35
	v_mul_f32_e32 v36, v40, v36
	v_mul_f32_e32 v37, v41, v37
	v_mul_f32_e32 v46, v134, v34
	v_mul_f32_e32 v47, v135, v35
	v_mul_f32_e32 v48, v136, v36
	v_mul_f32_e32 v49, v137, v37
	v_cvt_pk_bf16_f32 v50, v46, v47
	v_cvt_pk_bf16_f32 v51, v48, v49
	global_store_dwordx2 v182, v[50:51], s[12:13] offset:416
	v_lshlrev_b32_e32 v34, 16, v200
	v_and_b32_e32 v35, 0xffff0000, v200
	v_lshlrev_b32_e32 v36, 16, v201
	v_and_b32_e32 v37, 0xffff0000, v201
	v_mul_f32_e32 v38, v34, v34
	v_mul_f32_e32 v39, v35, v35
	v_mul_f32_e32 v40, v36, v36
	v_mul_f32_e32 v41, v37, v37
	v_fmaak_f32 v38, v38, v197, 0xc0135761
	v_fmaak_f32 v39, v39, v197, 0xc0135761
	v_fmaak_f32 v40, v40, v197, 0xc0135761
	v_fmaak_f32 v41, v41, v197, 0xc0135761
	v_mul_f32_e32 v38, v38, v34
	v_mul_f32_e32 v39, v39, v35
	v_mul_f32_e32 v40, v40, v36
	v_mul_f32_e32 v41, v41, v37
	v_exp_f32_e32 v38, v38
	v_exp_f32_e32 v39, v39
	v_exp_f32_e32 v40, v40
	v_exp_f32_e32 v41, v41
	v_add_f32_e32 v38, 1.0, v38
	v_add_f32_e32 v39, 1.0, v39
	v_add_f32_e32 v40, 1.0, v40
	v_add_f32_e32 v41, 1.0, v41
	v_rcp_f32_e32 v38, v38
	v_rcp_f32_e32 v39, v39
	v_rcp_f32_e32 v40, v40
	v_rcp_f32_e32 v41, v41
	v_mul_f32_e32 v34, v38, v34
	v_mul_f32_e32 v35, v39, v35
	v_mul_f32_e32 v36, v40, v36
	v_mul_f32_e32 v37, v41, v37
	v_mul_f32_e32 v46, v138, v34
	v_mul_f32_e32 v47, v139, v35
	v_mul_f32_e32 v48, v140, v36
	v_mul_f32_e32 v49, v141, v37
	v_cvt_pk_bf16_f32 v50, v46, v47
	v_cvt_pk_bf16_f32 v51, v48, v49
	global_store_dwordx2 v182, v[50:51], s[12:13] offset:448
	v_lshlrev_b32_e32 v34, 16, v202
	v_and_b32_e32 v35, 0xffff0000, v202
	v_lshlrev_b32_e32 v36, 16, v203
	v_and_b32_e32 v37, 0xffff0000, v203
	v_mul_f32_e32 v38, v34, v34
	v_mul_f32_e32 v39, v35, v35
	v_mul_f32_e32 v40, v36, v36
	v_mul_f32_e32 v41, v37, v37
	v_fmaak_f32 v38, v38, v197, 0xc0135761
	v_fmaak_f32 v39, v39, v197, 0xc0135761
	v_fmaak_f32 v40, v40, v197, 0xc0135761
	v_fmaak_f32 v41, v41, v197, 0xc0135761
	v_mul_f32_e32 v38, v38, v34
	v_mul_f32_e32 v39, v39, v35
	v_mul_f32_e32 v40, v40, v36
	v_mul_f32_e32 v41, v41, v37
	v_exp_f32_e32 v38, v38
	v_exp_f32_e32 v39, v39
	v_exp_f32_e32 v40, v40
	v_exp_f32_e32 v41, v41
	v_add_f32_e32 v38, 1.0, v38
	v_add_f32_e32 v39, 1.0, v39
	v_add_f32_e32 v40, 1.0, v40
	v_add_f32_e32 v41, 1.0, v41
	v_rcp_f32_e32 v38, v38
	v_rcp_f32_e32 v39, v39
	v_rcp_f32_e32 v40, v40
	v_rcp_f32_e32 v41, v41
	v_mul_f32_e32 v34, v38, v34
	v_mul_f32_e32 v35, v39, v35
	v_mul_f32_e32 v36, v40, v36
	v_mul_f32_e32 v37, v41, v37
	v_mul_f32_e32 v46, v160, v34
	v_mul_f32_e32 v47, v161, v35
	v_mul_f32_e32 v48, v162, v36
	v_mul_f32_e32 v49, v163, v37
	v_cvt_pk_bf16_f32 v50, v46, v47
	v_cvt_pk_bf16_f32 v51, v48, v49
	global_store_dwordx2 v182, v[50:51], s[12:13] offset:480
	s_add_i32 s2, s2, s3
	s_cmpk_lt_i32 s2, 0x100
	s_waitcnt lgkmcnt(0)
	s_barrier
	s_cbranch_scc1 .LBB0_330
	v_readfirstlane_b32 vcc_lo, v204
	s_nop 3
	s_lshr_b32 vcc_lo, vcc_lo, 6
	s_cmp_lt_u32 vcc_lo, 4
	s_cbranch_scc0 .Lprio_tm_done
	s_setprio 1
.Lprio_tm_done:
.LBB0_346:
	v_readlane_b32 s0, v248, 56
	s_add_i32 s2, s0, 3
	s_cmp_ge_i32 s2, s95
	s_cbranch_scc1 .LBB0_413
	v_readlane_b32 s6, v250, 54
	v_readlane_b32 s7, v250, 55
	s_mov_b64 s[0:1], -1
	s_and_b64 vcc, exec, s[6:7]
	s_cbranch_vccz .LBB0_401
	s_waitcnt vmcnt(0)
	s_waitcnt vmcnt(0) lgkmcnt(0)
	s_barrier
	s_mov_b64 s[0:1], exec
	v_readlane_b32 s6, v250, 34
	v_readlane_b32 s7, v250, 35
	s_and_b64 s[6:7], s[0:1], s[6:7]
	s_mov_b64 exec, s[6:7]
	s_cbranch_execz .LBB0_400
	v_readlane_b32 s4, v248, 48
	s_waitcnt vmcnt(0) expcnt(0) lgkmcnt(0)
	s_nop 0
	v_mov_b32_e32 v0, s4
	ds_read_b32 v3, v0
	v_readlane_b32 s4, v248, 49
	s_waitcnt lgkmcnt(0)
	v_cmp_ne_u32_e32 vcc, 0, v3
	v_mov_b32_e32 v0, s4
	ds_read_b32 v2, v0
	s_cbranch_vccnz .LBB0_364
	v_readlane_b32 s16, v250, 0
	v_readlane_b32 s17, v250, 1
	s_load_dwordx2 s[6:7], s[16:17], 0x4
	s_mov_b32 s20, 1
	s_waitcnt lgkmcnt(0)
	s_mul_i32 s4, s6, s3
	s_mul_i32 s4, s4, s7
	s_branch .LBB0_352
